# G1A q/k head-norm epilogue hand-written: batched cross-lane reduction (2 LDS round trips instead of 16), v_rsq_f32, in-place packed scaling
# speedup vs baseline: 1.0048x; 1.0048x over previous
.LBB0_27:
	s_cmp_lt_i32 s67, 6
	s_waitcnt lgkmcnt(0)
	s_cselect_b32 s0, s12, s14
	s_cselect_b32 s1, s13, s15
	s_cselect_b32 s4, 0x3e000000, 1.0
	v_ashrrev_i32_e32 v147, 31, v146
	v_lshl_add_u64 v[150:151], v[146:147], 2, s[0:1]
	global_load_dwordx4 v[128:131], v[150:151], off
	global_load_dwordx4 v[182:185], v[150:151], off offset:128
	global_load_dwordx4 v[186:189], v[150:151], off offset:144
	global_load_dwordx4 v[146:149], v[150:151], off offset:16
	v_xor_b32_e32 v152, 16, v171
	v_xor_b32_e32 v153, 32, v171
	v_lshlrev_b32_e32 v175, 2, v152
	v_lshlrev_b32_e32 v177, 2, v153
	v_lshlrev_b64 v[160:161], 1, v[160:161]
	v_mov_b64_e32 v[158:159], s[20:21]
	v_mad_i64_i32 v[190:191], s[0:1], v181, s64, v[158:159]
	v_lshl_add_u64 v[190:191], v[190:191], 0, v[160:161]
	v_pk_mul_f32 v[152:153], v[124:125], v[124:125]
	v_pk_mul_f32 v[154:155], v[116:117], v[116:117]
	v_pk_fma_f32 v[152:153], v[126:127], v[126:127], v[152:153]
	v_pk_fma_f32 v[154:155], v[118:119], v[118:119], v[154:155]
	v_pk_fma_f32 v[152:153], v[120:121], v[120:121], v[152:153]
	v_pk_fma_f32 v[154:155], v[112:113], v[112:113], v[154:155]
	v_pk_fma_f32 v[152:153], v[122:123], v[122:123], v[152:153]
	v_pk_fma_f32 v[154:155], v[114:115], v[114:115], v[154:155]
	v_pk_add_f32 v[152:153], v[152:153], v[154:155]
	v_add_f32_e32 v232, v152, v153
	v_pk_mul_f32 v[152:153], v[108:109], v[108:109]
	v_pk_mul_f32 v[154:155], v[100:101], v[100:101]
	v_pk_fma_f32 v[152:153], v[110:111], v[110:111], v[152:153]
	v_pk_fma_f32 v[154:155], v[102:103], v[102:103], v[154:155]
	v_pk_fma_f32 v[152:153], v[104:105], v[104:105], v[152:153]
	v_pk_fma_f32 v[154:155], v[96:97], v[96:97], v[154:155]
	v_pk_fma_f32 v[152:153], v[106:107], v[106:107], v[152:153]
	v_pk_fma_f32 v[154:155], v[98:99], v[98:99], v[154:155]
	v_pk_add_f32 v[152:153], v[152:153], v[154:155]
	v_add_f32_e32 v234, v152, v153
	v_pk_mul_f32 v[152:153], v[92:93], v[92:93]
	v_pk_mul_f32 v[154:155], v[84:85], v[84:85]
	v_pk_fma_f32 v[152:153], v[94:95], v[94:95], v[152:153]
	v_pk_fma_f32 v[154:155], v[86:87], v[86:87], v[154:155]
	v_pk_fma_f32 v[152:153], v[88:89], v[88:89], v[152:153]
	v_pk_fma_f32 v[154:155], v[80:81], v[80:81], v[154:155]
	v_pk_fma_f32 v[152:153], v[90:91], v[90:91], v[152:153]
	v_pk_fma_f32 v[154:155], v[82:83], v[82:83], v[154:155]
	v_pk_add_f32 v[152:153], v[152:153], v[154:155]
	v_add_f32_e32 v236, v152, v153
	v_pk_mul_f32 v[152:153], v[76:77], v[76:77]
	v_pk_mul_f32 v[154:155], v[68:69], v[68:69]
	v_pk_fma_f32 v[152:153], v[78:79], v[78:79], v[152:153]
	v_pk_fma_f32 v[154:155], v[70:71], v[70:71], v[154:155]
	v_pk_fma_f32 v[152:153], v[72:73], v[72:73], v[152:153]
	v_pk_fma_f32 v[154:155], v[64:65], v[64:65], v[154:155]
	v_pk_fma_f32 v[152:153], v[74:75], v[74:75], v[152:153]
	v_pk_fma_f32 v[154:155], v[66:67], v[66:67], v[154:155]
	v_pk_add_f32 v[152:153], v[152:153], v[154:155]
	v_add_f32_e32 v238, v152, v153
	v_pk_mul_f32 v[152:153], v[60:61], v[60:61]
	v_pk_mul_f32 v[154:155], v[52:53], v[52:53]
	v_pk_fma_f32 v[152:153], v[62:63], v[62:63], v[152:153]
	v_pk_fma_f32 v[154:155], v[54:55], v[54:55], v[154:155]
	v_pk_fma_f32 v[152:153], v[56:57], v[56:57], v[152:153]
	v_pk_fma_f32 v[154:155], v[48:49], v[48:49], v[154:155]
	v_pk_fma_f32 v[152:153], v[58:59], v[58:59], v[152:153]
	v_pk_fma_f32 v[154:155], v[50:51], v[50:51], v[154:155]
	v_pk_add_f32 v[152:153], v[152:153], v[154:155]
	v_add_f32_e32 v240, v152, v153
	v_pk_mul_f32 v[152:153], v[44:45], v[44:45]
	v_pk_mul_f32 v[154:155], v[36:37], v[36:37]
	v_pk_fma_f32 v[152:153], v[46:47], v[46:47], v[152:153]
	v_pk_fma_f32 v[154:155], v[38:39], v[38:39], v[154:155]
	v_pk_fma_f32 v[152:153], v[40:41], v[40:41], v[152:153]
	v_pk_fma_f32 v[154:155], v[32:33], v[32:33], v[154:155]
	v_pk_fma_f32 v[152:153], v[42:43], v[42:43], v[152:153]
	v_pk_fma_f32 v[154:155], v[34:35], v[34:35], v[154:155]
	v_pk_add_f32 v[152:153], v[152:153], v[154:155]
	v_add_f32_e32 v242, v152, v153
	v_pk_mul_f32 v[152:153], v[28:29], v[28:29]
	v_pk_mul_f32 v[154:155], v[20:21], v[20:21]
	v_pk_fma_f32 v[152:153], v[30:31], v[30:31], v[152:153]
	v_pk_fma_f32 v[154:155], v[22:23], v[22:23], v[154:155]
	v_pk_fma_f32 v[152:153], v[24:25], v[24:25], v[152:153]
	v_pk_fma_f32 v[154:155], v[16:17], v[16:17], v[154:155]
	v_pk_fma_f32 v[152:153], v[26:27], v[26:27], v[152:153]
	v_pk_fma_f32 v[154:155], v[18:19], v[18:19], v[154:155]
	v_pk_add_f32 v[152:153], v[152:153], v[154:155]
	v_add_f32_e32 v244, v152, v153
	v_pk_mul_f32 v[152:153], v[12:13], v[12:13]
	v_pk_mul_f32 v[154:155], v[4:5], v[4:5]
	v_pk_fma_f32 v[152:153], v[14:15], v[14:15], v[152:153]
	v_pk_fma_f32 v[154:155], v[6:7], v[6:7], v[154:155]
	v_pk_fma_f32 v[152:153], v[8:9], v[8:9], v[152:153]
	v_pk_fma_f32 v[154:155], v[0:1], v[0:1], v[154:155]
	v_pk_fma_f32 v[152:153], v[10:11], v[10:11], v[152:153]
	v_pk_fma_f32 v[154:155], v[2:3], v[2:3], v[154:155]
	v_pk_add_f32 v[152:153], v[152:153], v[154:155]
	v_add_f32_e32 v246, v152, v153
	ds_bpermute_b32 v233, v175, v232
	ds_bpermute_b32 v235, v175, v234
	ds_bpermute_b32 v237, v175, v236
	ds_bpermute_b32 v239, v175, v238
	ds_bpermute_b32 v241, v175, v240
	ds_bpermute_b32 v243, v175, v242
	ds_bpermute_b32 v245, v175, v244
	ds_bpermute_b32 v247, v175, v246
	s_waitcnt lgkmcnt(0)
	v_add_f32_e32 v232, v232, v233
	v_add_f32_e32 v234, v234, v235
	v_add_f32_e32 v236, v236, v237
	v_add_f32_e32 v238, v238, v239
	v_add_f32_e32 v240, v240, v241
	v_add_f32_e32 v242, v242, v243
	v_add_f32_e32 v244, v244, v245
	v_add_f32_e32 v246, v246, v247
	ds_bpermute_b32 v233, v177, v232
	ds_bpermute_b32 v235, v177, v234
	ds_bpermute_b32 v237, v177, v236
	ds_bpermute_b32 v239, v177, v238
	ds_bpermute_b32 v241, v177, v240
	ds_bpermute_b32 v243, v177, v242
	ds_bpermute_b32 v245, v177, v244
	ds_bpermute_b32 v247, v177, v246
	s_waitcnt lgkmcnt(0)
	v_add_f32_e32 v232, v232, v233
	v_add_f32_e32 v234, v234, v235
	v_add_f32_e32 v236, v236, v237
	v_add_f32_e32 v238, v238, v239
	v_add_f32_e32 v240, v240, v241
	v_add_f32_e32 v242, v242, v243
	v_add_f32_e32 v244, v244, v245
	v_add_f32_e32 v246, v246, v247
	v_fmamk_f32 v232, v232, 0x3c800000, v168
	v_fmamk_f32 v234, v234, 0x3c800000, v168
	v_fmamk_f32 v236, v236, 0x3c800000, v168
	v_fmamk_f32 v238, v238, 0x3c800000, v168
	v_fmamk_f32 v240, v240, 0x3c800000, v168
	v_fmamk_f32 v242, v242, 0x3c800000, v168
	v_fmamk_f32 v244, v244, 0x3c800000, v168
	v_fmamk_f32 v246, v246, 0x3c800000, v168
	v_rsq_f32_e32 v232, v232
	v_rsq_f32_e32 v234, v234
	v_rsq_f32_e32 v236, v236
	v_rsq_f32_e32 v238, v238
	v_rsq_f32_e32 v240, v240
	v_rsq_f32_e32 v242, v242
	v_rsq_f32_e32 v244, v244
	v_rsq_f32_e32 v246, v246
	s_waitcnt vmcnt(0)
	v_pk_mul_f32 v[128:129], v[128:129], s[4:5] op_sel_hi:[1,0]
	v_pk_mul_f32 v[130:131], v[130:131], s[4:5] op_sel_hi:[1,0]
	v_pk_mul_f32 v[146:147], v[146:147], s[4:5] op_sel_hi:[1,0]
	v_pk_mul_f32 v[148:149], v[148:149], s[4:5] op_sel_hi:[1,0]
	v_pk_mul_f32 v[182:183], v[182:183], s[4:5] op_sel_hi:[1,0]
	v_pk_mul_f32 v[184:185], v[184:185], s[4:5] op_sel_hi:[1,0]
	v_pk_mul_f32 v[186:187], v[186:187], s[4:5] op_sel_hi:[1,0]
	v_pk_mul_f32 v[188:189], v[188:189], s[4:5] op_sel_hi:[1,0]
	v_pk_mul_f32 v[124:125], v[124:125], v[232:233] op_sel_hi:[1,0]
	v_pk_mul_f32 v[126:127], v[126:127], v[232:233] op_sel_hi:[1,0]
	v_pk_mul_f32 v[120:121], v[120:121], v[232:233] op_sel_hi:[1,0]
	v_pk_mul_f32 v[122:123], v[122:123], v[232:233] op_sel_hi:[1,0]
	v_pk_mul_f32 v[116:117], v[116:117], v[232:233] op_sel_hi:[1,0]
	v_pk_mul_f32 v[118:119], v[118:119], v[232:233] op_sel_hi:[1,0]
	v_pk_mul_f32 v[112:113], v[112:113], v[232:233] op_sel_hi:[1,0]
	v_pk_mul_f32 v[114:115], v[114:115], v[232:233] op_sel_hi:[1,0]
	v_pk_mul_f32 v[124:125], v[124:125], v[128:129]
	v_pk_mul_f32 v[126:127], v[126:127], v[130:131]
	v_pk_mul_f32 v[120:121], v[120:121], v[146:147]
	v_pk_mul_f32 v[122:123], v[122:123], v[148:149]
	v_pk_mul_f32 v[116:117], v[116:117], v[182:183]
	v_pk_mul_f32 v[118:119], v[118:119], v[184:185]
	v_pk_mul_f32 v[112:113], v[112:113], v[186:187]
	v_pk_mul_f32 v[114:115], v[114:115], v[188:189]
	v_cvt_pk_bf16_f32 v124, v124, v125
	v_cvt_pk_bf16_f32 v125, v126, v127
	v_cvt_pk_bf16_f32 v126, v120, v121
	v_cvt_pk_bf16_f32 v127, v122, v123
	v_cvt_pk_bf16_f32 v116, v116, v117
	v_cvt_pk_bf16_f32 v117, v118, v119
	v_cvt_pk_bf16_f32 v118, v112, v113
	v_cvt_pk_bf16_f32 v119, v114, v115
	global_store_dwordx4 v[190:191], v[124:127], off
	global_store_dwordx4 v[190:191], v[116:119], off offset:64
	v_pk_mul_f32 v[108:109], v[108:109], v[234:235] op_sel_hi:[1,0]
	v_pk_mul_f32 v[110:111], v[110:111], v[234:235] op_sel_hi:[1,0]
	v_pk_mul_f32 v[104:105], v[104:105], v[234:235] op_sel_hi:[1,0]
	v_pk_mul_f32 v[106:107], v[106:107], v[234:235] op_sel_hi:[1,0]
	v_pk_mul_f32 v[100:101], v[100:101], v[234:235] op_sel_hi:[1,0]
	v_pk_mul_f32 v[102:103], v[102:103], v[234:235] op_sel_hi:[1,0]
	v_pk_mul_f32 v[96:97], v[96:97], v[234:235] op_sel_hi:[1,0]
	v_pk_mul_f32 v[98:99], v[98:99], v[234:235] op_sel_hi:[1,0]
	v_pk_mul_f32 v[108:109], v[108:109], v[128:129]
	v_pk_mul_f32 v[110:111], v[110:111], v[130:131]
	v_pk_mul_f32 v[104:105], v[104:105], v[146:147]
	v_pk_mul_f32 v[106:107], v[106:107], v[148:149]
	v_pk_mul_f32 v[100:101], v[100:101], v[182:183]
	v_pk_mul_f32 v[102:103], v[102:103], v[184:185]
	v_pk_mul_f32 v[96:97], v[96:97], v[186:187]
	v_pk_mul_f32 v[98:99], v[98:99], v[188:189]
	v_cvt_pk_bf16_f32 v108, v108, v109
	v_cvt_pk_bf16_f32 v109, v110, v111
	v_cvt_pk_bf16_f32 v110, v104, v105
	v_cvt_pk_bf16_f32 v111, v106, v107
	v_cvt_pk_bf16_f32 v100, v100, v101
	v_cvt_pk_bf16_f32 v101, v102, v103
	v_cvt_pk_bf16_f32 v102, v96, v97
	v_cvt_pk_bf16_f32 v103, v98, v99
	s_mov_b64 s[98:99], 0x24000
	v_lshl_add_u64 v[192:193], v[190:191], 0, s[98:99]
	global_store_dwordx4 v[192:193], v[108:111], off
	global_store_dwordx4 v[192:193], v[100:103], off offset:64
	v_pk_mul_f32 v[92:93], v[92:93], v[236:237] op_sel_hi:[1,0]
	v_pk_mul_f32 v[94:95], v[94:95], v[236:237] op_sel_hi:[1,0]
	v_pk_mul_f32 v[88:89], v[88:89], v[236:237] op_sel_hi:[1,0]
	v_pk_mul_f32 v[90:91], v[90:91], v[236:237] op_sel_hi:[1,0]
	v_pk_mul_f32 v[84:85], v[84:85], v[236:237] op_sel_hi:[1,0]
	v_pk_mul_f32 v[86:87], v[86:87], v[236:237] op_sel_hi:[1,0]
	v_pk_mul_f32 v[80:81], v[80:81], v[236:237] op_sel_hi:[1,0]
	v_pk_mul_f32 v[82:83], v[82:83], v[236:237] op_sel_hi:[1,0]
	v_pk_mul_f32 v[92:93], v[92:93], v[128:129]
	v_pk_mul_f32 v[94:95], v[94:95], v[130:131]
	v_pk_mul_f32 v[88:89], v[88:89], v[146:147]
	v_pk_mul_f32 v[90:91], v[90:91], v[148:149]
	v_pk_mul_f32 v[84:85], v[84:85], v[182:183]
	v_pk_mul_f32 v[86:87], v[86:87], v[184:185]
	v_pk_mul_f32 v[80:81], v[80:81], v[186:187]
	v_pk_mul_f32 v[82:83], v[82:83], v[188:189]
	v_cvt_pk_bf16_f32 v92, v92, v93
	v_cvt_pk_bf16_f32 v93, v94, v95
	v_cvt_pk_bf16_f32 v94, v88, v89
	v_cvt_pk_bf16_f32 v95, v90, v91
	v_cvt_pk_bf16_f32 v84, v84, v85
	v_cvt_pk_bf16_f32 v85, v86, v87
	v_cvt_pk_bf16_f32 v86, v80, v81
	v_cvt_pk_bf16_f32 v87, v82, v83
	s_mov_b64 s[98:99], 0x48000
	v_lshl_add_u64 v[192:193], v[190:191], 0, s[98:99]
	global_store_dwordx4 v[192:193], v[92:95], off
	global_store_dwordx4 v[192:193], v[84:87], off offset:64
	v_pk_mul_f32 v[76:77], v[76:77], v[238:239] op_sel_hi:[1,0]
	v_pk_mul_f32 v[78:79], v[78:79], v[238:239] op_sel_hi:[1,0]
	v_pk_mul_f32 v[72:73], v[72:73], v[238:239] op_sel_hi:[1,0]
	v_pk_mul_f32 v[74:75], v[74:75], v[238:239] op_sel_hi:[1,0]
	v_pk_mul_f32 v[68:69], v[68:69], v[238:239] op_sel_hi:[1,0]
	v_pk_mul_f32 v[70:71], v[70:71], v[238:239] op_sel_hi:[1,0]
	v_pk_mul_f32 v[64:65], v[64:65], v[238:239] op_sel_hi:[1,0]
	v_pk_mul_f32 v[66:67], v[66:67], v[238:239] op_sel_hi:[1,0]
	v_pk_mul_f32 v[76:77], v[76:77], v[128:129]
	v_pk_mul_f32 v[78:79], v[78:79], v[130:131]
	v_pk_mul_f32 v[72:73], v[72:73], v[146:147]
	v_pk_mul_f32 v[74:75], v[74:75], v[148:149]
	v_pk_mul_f32 v[68:69], v[68:69], v[182:183]
	v_pk_mul_f32 v[70:71], v[70:71], v[184:185]
	v_pk_mul_f32 v[64:65], v[64:65], v[186:187]
	v_pk_mul_f32 v[66:67], v[66:67], v[188:189]
	v_cvt_pk_bf16_f32 v76, v76, v77
	v_cvt_pk_bf16_f32 v77, v78, v79
	v_cvt_pk_bf16_f32 v78, v72, v73
	v_cvt_pk_bf16_f32 v79, v74, v75
	v_cvt_pk_bf16_f32 v68, v68, v69
	v_cvt_pk_bf16_f32 v69, v70, v71
	v_cvt_pk_bf16_f32 v70, v64, v65
	v_cvt_pk_bf16_f32 v71, v66, v67
	s_mov_b64 s[98:99], 0x6c000
	v_lshl_add_u64 v[192:193], v[190:191], 0, s[98:99]
	global_store_dwordx4 v[192:193], v[76:79], off
	global_store_dwordx4 v[192:193], v[68:71], off offset:64
	v_pk_mul_f32 v[60:61], v[60:61], v[240:241] op_sel_hi:[1,0]
	v_pk_mul_f32 v[62:63], v[62:63], v[240:241] op_sel_hi:[1,0]
	v_pk_mul_f32 v[56:57], v[56:57], v[240:241] op_sel_hi:[1,0]
	v_pk_mul_f32 v[58:59], v[58:59], v[240:241] op_sel_hi:[1,0]
	v_pk_mul_f32 v[52:53], v[52:53], v[240:241] op_sel_hi:[1,0]
	v_pk_mul_f32 v[54:55], v[54:55], v[240:241] op_sel_hi:[1,0]
	v_pk_mul_f32 v[48:49], v[48:49], v[240:241] op_sel_hi:[1,0]
	v_pk_mul_f32 v[50:51], v[50:51], v[240:241] op_sel_hi:[1,0]
	v_pk_mul_f32 v[60:61], v[60:61], v[128:129]
	v_pk_mul_f32 v[62:63], v[62:63], v[130:131]
	v_pk_mul_f32 v[56:57], v[56:57], v[146:147]
	v_pk_mul_f32 v[58:59], v[58:59], v[148:149]
	v_pk_mul_f32 v[52:53], v[52:53], v[182:183]
	v_pk_mul_f32 v[54:55], v[54:55], v[184:185]
	v_pk_mul_f32 v[48:49], v[48:49], v[186:187]
	v_pk_mul_f32 v[50:51], v[50:51], v[188:189]
	v_cvt_pk_bf16_f32 v60, v60, v61
	v_cvt_pk_bf16_f32 v61, v62, v63
	v_cvt_pk_bf16_f32 v62, v56, v57
	v_cvt_pk_bf16_f32 v63, v58, v59
	v_cvt_pk_bf16_f32 v52, v52, v53
	v_cvt_pk_bf16_f32 v53, v54, v55
	v_cvt_pk_bf16_f32 v54, v48, v49
	v_cvt_pk_bf16_f32 v55, v50, v51
	s_mov_b64 s[98:99], 0x120000
	v_lshl_add_u64 v[192:193], v[190:191], 0, s[98:99]
	global_store_dwordx4 v[192:193], v[60:63], off
	global_store_dwordx4 v[192:193], v[52:55], off offset:64
	v_pk_mul_f32 v[44:45], v[44:45], v[242:243] op_sel_hi:[1,0]
	v_pk_mul_f32 v[46:47], v[46:47], v[242:243] op_sel_hi:[1,0]
	v_pk_mul_f32 v[40:41], v[40:41], v[242:243] op_sel_hi:[1,0]
	v_pk_mul_f32 v[42:43], v[42:43], v[242:243] op_sel_hi:[1,0]
	v_pk_mul_f32 v[36:37], v[36:37], v[242:243] op_sel_hi:[1,0]
	v_pk_mul_f32 v[38:39], v[38:39], v[242:243] op_sel_hi:[1,0]
	v_pk_mul_f32 v[32:33], v[32:33], v[242:243] op_sel_hi:[1,0]
	v_pk_mul_f32 v[34:35], v[34:35], v[242:243] op_sel_hi:[1,0]
	v_pk_mul_f32 v[44:45], v[44:45], v[128:129]
	v_pk_mul_f32 v[46:47], v[46:47], v[130:131]
	v_pk_mul_f32 v[40:41], v[40:41], v[146:147]
	v_pk_mul_f32 v[42:43], v[42:43], v[148:149]
	v_pk_mul_f32 v[36:37], v[36:37], v[182:183]
	v_pk_mul_f32 v[38:39], v[38:39], v[184:185]
	v_pk_mul_f32 v[32:33], v[32:33], v[186:187]
	v_pk_mul_f32 v[34:35], v[34:35], v[188:189]
	v_cvt_pk_bf16_f32 v44, v44, v45
	v_cvt_pk_bf16_f32 v45, v46, v47
	v_cvt_pk_bf16_f32 v46, v40, v41
	v_cvt_pk_bf16_f32 v47, v42, v43
	v_cvt_pk_bf16_f32 v36, v36, v37
	v_cvt_pk_bf16_f32 v37, v38, v39
	v_cvt_pk_bf16_f32 v38, v32, v33
	v_cvt_pk_bf16_f32 v39, v34, v35
	s_mov_b64 s[98:99], 0x144000
	v_lshl_add_u64 v[192:193], v[190:191], 0, s[98:99]
	global_store_dwordx4 v[192:193], v[44:47], off
	global_store_dwordx4 v[192:193], v[36:39], off offset:64
	v_pk_mul_f32 v[28:29], v[28:29], v[244:245] op_sel_hi:[1,0]
	v_pk_mul_f32 v[30:31], v[30:31], v[244:245] op_sel_hi:[1,0]
	v_pk_mul_f32 v[24:25], v[24:25], v[244:245] op_sel_hi:[1,0]
	v_pk_mul_f32 v[26:27], v[26:27], v[244:245] op_sel_hi:[1,0]
	v_pk_mul_f32 v[20:21], v[20:21], v[244:245] op_sel_hi:[1,0]
	v_pk_mul_f32 v[22:23], v[22:23], v[244:245] op_sel_hi:[1,0]
	v_pk_mul_f32 v[16:17], v[16:17], v[244:245] op_sel_hi:[1,0]
	v_pk_mul_f32 v[18:19], v[18:19], v[244:245] op_sel_hi:[1,0]
	v_pk_mul_f32 v[28:29], v[28:29], v[128:129]
	v_pk_mul_f32 v[30:31], v[30:31], v[130:131]
	v_pk_mul_f32 v[24:25], v[24:25], v[146:147]
	v_pk_mul_f32 v[26:27], v[26:27], v[148:149]
	v_pk_mul_f32 v[20:21], v[20:21], v[182:183]
	v_pk_mul_f32 v[22:23], v[22:23], v[184:185]
	v_pk_mul_f32 v[16:17], v[16:17], v[186:187]
	v_pk_mul_f32 v[18:19], v[18:19], v[188:189]
	v_cvt_pk_bf16_f32 v28, v28, v29
	v_cvt_pk_bf16_f32 v29, v30, v31
	v_cvt_pk_bf16_f32 v30, v24, v25
	v_cvt_pk_bf16_f32 v31, v26, v27
	v_cvt_pk_bf16_f32 v20, v20, v21
	v_cvt_pk_bf16_f32 v21, v22, v23
	v_cvt_pk_bf16_f32 v22, v16, v17
	v_cvt_pk_bf16_f32 v23, v18, v19
	s_mov_b64 s[98:99], 0x168000
	v_lshl_add_u64 v[192:193], v[190:191], 0, s[98:99]
	global_store_dwordx4 v[192:193], v[28:31], off
	global_store_dwordx4 v[192:193], v[20:23], off offset:64
	v_pk_mul_f32 v[12:13], v[12:13], v[246:247] op_sel_hi:[1,0]
	v_pk_mul_f32 v[14:15], v[14:15], v[246:247] op_sel_hi:[1,0]
	v_pk_mul_f32 v[8:9], v[8:9], v[246:247] op_sel_hi:[1,0]
	v_pk_mul_f32 v[10:11], v[10:11], v[246:247] op_sel_hi:[1,0]
	v_pk_mul_f32 v[4:5], v[4:5], v[246:247] op_sel_hi:[1,0]
	v_pk_mul_f32 v[6:7], v[6:7], v[246:247] op_sel_hi:[1,0]
	v_pk_mul_f32 v[0:1], v[0:1], v[246:247] op_sel_hi:[1,0]
	v_pk_mul_f32 v[2:3], v[2:3], v[246:247] op_sel_hi:[1,0]
	v_pk_mul_f32 v[12:13], v[12:13], v[128:129]
	v_pk_mul_f32 v[14:15], v[14:15], v[130:131]
	v_pk_mul_f32 v[8:9], v[8:9], v[146:147]
	v_pk_mul_f32 v[10:11], v[10:11], v[148:149]
	v_pk_mul_f32 v[4:5], v[4:5], v[182:183]
	v_pk_mul_f32 v[6:7], v[6:7], v[184:185]
	v_pk_mul_f32 v[0:1], v[0:1], v[186:187]
	v_pk_mul_f32 v[2:3], v[2:3], v[188:189]
	v_cvt_pk_bf16_f32 v12, v12, v13
	v_cvt_pk_bf16_f32 v13, v14, v15
	v_cvt_pk_bf16_f32 v14, v8, v9
	v_cvt_pk_bf16_f32 v15, v10, v11
	v_cvt_pk_bf16_f32 v4, v4, v5
	v_cvt_pk_bf16_f32 v5, v6, v7
	v_cvt_pk_bf16_f32 v6, v0, v1
	v_cvt_pk_bf16_f32 v7, v2, v3
	s_mov_b64 s[98:99], 0x18c000
	v_lshl_add_u64 v[192:193], v[190:191], 0, s[98:99]
	global_store_dwordx4 v[192:193], v[12:15], off
	s_and_b64 vcc, exec, s[2:3]
	s_mov_b64 s[2:3], -1
	global_store_dwordx4 v[192:193], v[4:7], off offset:64
	s_cbranch_vccnz .LBB0_11
